# v16 + phase 0: norm_rows row->wave order reversed so the waves with the extra conversion item do not also take the extra row
# baseline (speedup 1.0000x reference)
.LBB0_24:
	v_readlane_b32 s4, v248, 43
	v_and_b32_e32 v82, 63, v0
	s_sub_i32 s8, 0x7ff, s4
	s_cmpk_gt_i32 s8, 0x20ff
	s_cbranch_scc1 .LBB0_29
	v_mbcnt_lo_u32_b32 v1, -1, 0
	v_mbcnt_hi_u32_b32 v1, -1, v1
	v_and_b32_e32 v2, 64, v1
	s_load_dwordx16 s[12:27], s[0:1], 0x0
	v_add_u32_e32 v2, 64, v2
	v_xor_b32_e32 v3, 1, v1
	v_readlane_b32 s4, v248, 44
	v_ashrrev_i32_e32 v83, 31, v82
	v_cmp_lt_i32_e32 vcc, v3, v2
	v_readlane_b32 s5, v248, 45
	s_waitcnt lgkmcnt(0)
	v_lshl_add_u64 v[88:89], v[82:83], 4, s[24:25]
	v_cndmask_b32_e32 v3, v1, v3, vcc
	v_lshl_add_u64 v[84:85], v[82:83], 3, s[4:5]
	v_readlane_b32 s4, v248, 50
	v_lshlrev_b32_e32 v115, 2, v3
	v_xor_b32_e32 v3, 2, v1
	v_readlane_b32 s5, v248, 51
	v_cmp_lt_i32_e32 vcc, v3, v2
	s_ashr_i32 s9, s8, 31
	v_lshl_add_u64 v[86:87], v[82:83], 2, s[4:5]
	s_mov_b64 s[4:5], 0x1000
	v_cndmask_b32_e32 v3, v1, v3, vcc
	v_lshl_add_u64 v[90:91], v[88:89], 0, s[4:5]
	s_mov_b64 s[4:5], 0x1400
	v_lshlrev_b32_e32 v118, 2, v3
	v_xor_b32_e32 v3, 4, v1
	v_lshl_add_u64 v[92:93], v[88:89], 0, s[4:5]
	s_mov_b64 s[4:5], 0x1800
	v_cmp_lt_i32_e32 vcc, v3, v2
	v_lshl_add_u64 v[94:95], v[88:89], 0, s[4:5]
	s_mov_b64 s[4:5], 0x1c00
	v_cndmask_b32_e32 v3, v1, v3, vcc
	v_lshl_add_u64 v[96:97], v[88:89], 0, s[4:5]
	s_mov_b64 s[4:5], 0x2000
	v_lshlrev_b32_e32 v119, 2, v3
	v_xor_b32_e32 v3, 8, v1
	v_lshl_add_u64 v[98:99], v[88:89], 0, s[4:5]
	s_mov_b64 s[4:5], 0x2400
	v_cmp_lt_i32_e32 vcc, v3, v2
	v_lshl_add_u64 v[100:101], v[88:89], 0, s[4:5]
	s_mov_b64 s[4:5], 0x2800
	v_cndmask_b32_e32 v3, v1, v3, vcc
	v_lshl_add_u64 v[102:103], v[88:89], 0, s[4:5]
	s_mov_b64 s[4:5], 0x2c00
	v_lshlrev_b32_e32 v120, 2, v3
	v_xor_b32_e32 v3, 16, v1
	v_lshl_add_u64 v[104:105], v[88:89], 0, s[4:5]
	s_mov_b64 s[4:5], 0x3000
	v_cmp_lt_i32_e32 vcc, v3, v2
	v_lshl_add_u64 v[106:107], v[88:89], 0, s[4:5]
	s_mov_b64 s[4:5], 0x3400
	v_cndmask_b32_e32 v3, v1, v3, vcc
	v_lshl_add_u64 v[108:109], v[88:89], 0, s[4:5]
	s_mov_b64 s[4:5], 0x3800
	v_lshlrev_b32_e32 v121, 2, v3
	v_xor_b32_e32 v3, 32, v1
	v_lshl_add_u64 v[110:111], v[88:89], 0, s[4:5]
	s_mov_b64 s[4:5], 0x3c00
	v_cmp_lt_i32_e32 vcc, v3, v2
	v_lshl_add_u64 v[112:113], v[88:89], 0, s[4:5]
	s_ashr_i32 s67, s66, 31
	s_lshl_b64 s[4:5], s[8:9], 14
	v_cndmask_b32_e32 v1, v1, v3, vcc
	s_add_u32 s12, s12, s4
	s_mov_b32 s11, 0
	v_lshlrev_b32_e32 v122, 2, v1
	s_addc_u32 s13, s13, s5
	s_lshl_b64 s[14:15], s[66:67], 14
	s_movk_i32 s18, 0x2000
	s_movk_i32 s19, 0x1000
	s_movk_i32 s20, 0x3000
	v_mov_b32_e32 v123, 0x358637bd
	s_mov_b32 s21, 0xf800000
	v_mov_b32_e32 v124, 0x260
	s_branch .LBB0_27
